# attention: exp argument via packed f32 fma (16 instead of 32 per tile)
# speedup vs baseline: 1.0057x; 1.0035x over previous
.LBB0_786:
	v_lshrrev_b32_e32 v235, 6, v186
	v_and_b32_e32 v236, 63, v186
	v_readfirstlane_b32 s3, v235
	v_and_b32_e32 v237, 31, v236
	v_lshrrev_b32_e32 v238, 5, v236
	v_lshlrev_b32_e32 v229, 2, v238
	v_lshrrev_b32_e32 v239, 3, v186
	v_and_b32_e32 v240, 7, v186
	v_mul_u32_u24_e32 v33, 0x2cb0, v239
	v_bfe_u32 v241, v239, 1, 3
	v_xor_b32_e32 v241, v240, v241
	v_lshl_add_u32 v221, v241, 4, v33
	v_add_u32_e32 v221, 0x400, v221
	v_bfe_u32 v241, v239, 1, 1
	v_lshlrev_b32_e32 v241, 2, v241
	v_xor_b32_e32 v241, v240, v241
	v_lshl_add_u32 v222, v241, 4, v33
	v_add_u32_e32 v222, 0x800, v222
	v_bfe_u32 v241, v237, 1, 3
	v_or_b32_e32 v242, 0, v238
	v_xor_b32_e32 v242, v242, v241
	v_lshlrev_b32_e32 v242, 4, v242
	v_lshl_add_u32 v223, v237, 7, v242
	v_or_b32_e32 v242, 2, v238
	v_xor_b32_e32 v242, v242, v241
	v_lshlrev_b32_e32 v242, 4, v242
	v_lshl_add_u32 v224, v237, 7, v242
	v_or_b32_e32 v242, 4, v238
	v_xor_b32_e32 v242, v242, v241
	v_lshlrev_b32_e32 v242, 4, v242
	v_lshl_add_u32 v225, v237, 7, v242
	v_or_b32_e32 v242, 6, v238
	v_xor_b32_e32 v242, v242, v241
	v_lshlrev_b32_e32 v242, 4, v242
	v_lshl_add_u32 v226, v237, 7, v242
	v_and_b32_e32 v239, 3, v236
	v_bfe_u32 v240, v236, 2, 2
	v_bfe_u32 v241, v236, 4, 1
	v_lshrrev_b32_e32 v242, 1, v239
	v_lshl_add_u32 v241, v241, 1, v242
	v_lshrrev_b32_e32 v242, 1, v240
	v_lshl_add_u32 v33, v242, 2, v241
	v_xor_b32_e32 v242, 1, v242
	v_lshl_add_u32 v197, v242, 2, v241
	v_lshl_add_u32 v240, v238, 2, v240
	v_and_b32_e32 v239, 1, v239
	v_lshlrev_b32_e32 v239, 3, v239
	v_lshl_add_u32 v240, v240, 7, v239
	v_lshl_add_u32 v227, v33, 4, v240
	v_lshl_add_u32 v228, v197, 4, v240
	v_add_u32_e32 v227, 0x8000, v227
	v_add_u32_e32 v228, 0x8000, v228
	v_mov_b32_e32 v206, 0x3e38aa3b
	s_lshl_b32 s58, s3, 10
	s_cmp_lt_u32 s3, 4
	s_cbranch_scc1 .Lat_noprio
	s_setprio 1

.Lat_nors_f0:
	v_pk_fma_f32 v[34:35], v[34:35], v[206:207], v[234:235] op_sel_hi:[1,0,0]
	v_pk_fma_f32 v[36:37], v[36:37], v[206:207], v[234:235] op_sel_hi:[1,0,0]
	s_waitcnt lgkmcnt(7)
	v_mfma_f32_32x32x16_bf16 v[70:85], v[118:121], v[102:105], 0
	ds_read_b64_tr_b16 v[154:155], v227 offset:0
	ds_read_b64_tr_b16 v[156:157], v227 offset:1024
	v_pk_fma_f32 v[38:39], v[38:39], v[206:207], v[234:235] op_sel_hi:[1,0,0]
	v_pk_fma_f32 v[40:41], v[40:41], v[206:207], v[234:235] op_sel_hi:[1,0,0]
	v_exp_f32_e32 v34, v34
	v_exp_f32_e32 v35, v35
	v_exp_f32_e32 v36, v36
	v_exp_f32_e32 v37, v37
	v_exp_f32_e32 v38, v38
	v_exp_f32_e32 v39, v39
	s_waitcnt lgkmcnt(8)
	v_mfma_f32_32x32x16_bf16 v[86:101], v[122:125], v[102:105], 0
	ds_read_b64_tr_b16 v[158:159], v228 offset:0
	ds_read_b64_tr_b16 v[160:161], v228 offset:1024
	v_exp_f32_e32 v40, v40
	v_exp_f32_e32 v41, v41
	v_pk_add_f32 v[244:245], v[34:35], v[38:39]
	v_pk_add_f32 v[246:247], v[36:37], v[40:41]
	v_cvt_pk_bf16_f32 v34, v34, v35
	v_cvt_pk_bf16_f32 v35, v36, v37
	v_cvt_pk_bf16_f32 v36, v38, v39
	v_cvt_pk_bf16_f32 v37, v40, v41
	v_pk_fma_f32 v[42:43], v[42:43], v[206:207], v[234:235] op_sel_hi:[1,0,0]
	s_waitcnt lgkmcnt(9)
	v_mfma_f32_32x32x16_bf16 v[70:85], v[126:129], v[106:109], v[70:85]
	ds_read_b64_tr_b16 v[162:163], v227 offset:2048
	ds_read_b64_tr_b16 v[164:165], v227 offset:3072
	v_pk_fma_f32 v[44:45], v[44:45], v[206:207], v[234:235] op_sel_hi:[1,0,0]
	v_pk_fma_f32 v[46:47], v[46:47], v[206:207], v[234:235] op_sel_hi:[1,0,0]
	v_pk_fma_f32 v[48:49], v[48:49], v[206:207], v[234:235] op_sel_hi:[1,0,0]
	v_exp_f32_e32 v42, v42
	v_exp_f32_e32 v43, v43
	v_exp_f32_e32 v44, v44
	v_exp_f32_e32 v45, v45
	v_exp_f32_e32 v46, v46
	v_exp_f32_e32 v47, v47
	s_waitcnt lgkmcnt(10)
	v_mfma_f32_32x32x16_bf16 v[86:101], v[130:133], v[106:109], v[86:101]
	ds_read_b64_tr_b16 v[166:167], v228 offset:2048
	ds_read_b64_tr_b16 v[168:169], v228 offset:3072
	v_exp_f32_e32 v48, v48
	v_exp_f32_e32 v49, v49
	v_pk_add_f32 v[244:245], v[244:245], v[42:43]
	v_pk_add_f32 v[246:247], v[246:247], v[44:45]
	v_pk_add_f32 v[244:245], v[244:245], v[46:47]
	v_pk_add_f32 v[246:247], v[246:247], v[48:49]
	v_cvt_pk_bf16_f32 v42, v42, v43
	v_cvt_pk_bf16_f32 v43, v44, v45
	v_cvt_pk_bf16_f32 v44, v46, v47
	s_waitcnt lgkmcnt(11)
	v_mfma_f32_32x32x16_bf16 v[70:85], v[134:137], v[110:113], v[70:85]
	ds_read_b64_tr_b16 v[170:171], v227 offset:4096
	ds_read_b64_tr_b16 v[172:173], v227 offset:5120
	v_cvt_pk_bf16_f32 v45, v48, v49
	v_pk_fma_f32 v[50:51], v[50:51], v[206:207], v[234:235] op_sel_hi:[1,0,0]
	v_pk_fma_f32 v[52:53], v[52:53], v[206:207], v[234:235] op_sel_hi:[1,0,0]
	v_pk_fma_f32 v[54:55], v[54:55], v[206:207], v[234:235] op_sel_hi:[1,0,0]
	v_pk_fma_f32 v[56:57], v[56:57], v[206:207], v[234:235] op_sel_hi:[1,0,0]
	v_exp_f32_e32 v50, v50
	v_exp_f32_e32 v51, v51
	v_exp_f32_e32 v52, v52
	v_exp_f32_e32 v53, v53
	s_waitcnt lgkmcnt(12)
	v_mfma_f32_32x32x16_bf16 v[86:101], v[138:141], v[110:113], v[86:101]
	ds_read_b64_tr_b16 v[174:175], v228 offset:4096
	ds_read_b64_tr_b16 v[176:177], v228 offset:5120
	v_exp_f32_e32 v54, v54
	v_exp_f32_e32 v55, v55
	v_exp_f32_e32 v56, v56
	v_exp_f32_e32 v57, v57
	v_pk_add_f32 v[244:245], v[244:245], v[50:51]
	v_pk_add_f32 v[246:247], v[246:247], v[52:53]
	v_pk_add_f32 v[244:245], v[244:245], v[54:55]
	v_pk_add_f32 v[246:247], v[246:247], v[56:57]
	v_cvt_pk_bf16_f32 v50, v50, v51
	s_waitcnt lgkmcnt(13)
	v_mfma_f32_32x32x16_bf16 v[70:85], v[142:145], v[114:117], v[70:85]
	ds_read_b64_tr_b16 v[178:179], v227 offset:6144
	ds_read_b64_tr_b16 v[180:181], v227 offset:7168
	v_cvt_pk_bf16_f32 v51, v52, v53
	v_cvt_pk_bf16_f32 v52, v54, v55
	v_cvt_pk_bf16_f32 v53, v56, v57
	v_pk_fma_f32 v[58:59], v[58:59], v[206:207], v[234:235] op_sel_hi:[1,0,0]
	v_pk_fma_f32 v[60:61], v[60:61], v[206:207], v[234:235] op_sel_hi:[1,0,0]
	v_pk_fma_f32 v[62:63], v[62:63], v[206:207], v[234:235] op_sel_hi:[1,0,0]
	v_pk_fma_f32 v[64:65], v[64:65], v[206:207], v[234:235] op_sel_hi:[1,0,0]
	v_exp_f32_e32 v58, v58
	v_exp_f32_e32 v59, v59
	s_waitcnt lgkmcnt(14)
	v_mfma_f32_32x32x16_bf16 v[86:101], v[146:149], v[114:117], v[86:101]
	ds_read_b64_tr_b16 v[182:183], v228 offset:6144
	ds_read_b64_tr_b16 v[184:185], v228 offset:7168
	s_waitcnt lgkmcnt(14)
	v_exp_f32_e32 v60, v60
	v_exp_f32_e32 v61, v61
	v_exp_f32_e32 v62, v62
	v_exp_f32_e32 v63, v63
	v_exp_f32_e32 v64, v64
	v_exp_f32_e32 v65, v65
	v_pk_add_f32 v[244:245], v[244:245], v[58:59]
	v_pk_add_f32 v[246:247], v[246:247], v[60:61]
	s_waitcnt lgkmcnt(14)
	v_mfma_f32_32x32x16_bf16 v[0:15], v[154:157], v[34:37], v[0:15]
	ds_read_b128 v[118:121], v223 offset:16384
	v_pk_add_f32 v[244:245], v[244:245], v[62:63]
	v_pk_add_f32 v[246:247], v[246:247], v[64:65]
	v_cvt_pk_bf16_f32 v58, v58, v59
	v_cvt_pk_bf16_f32 v59, v60, v61
	v_cvt_pk_bf16_f32 v60, v62, v63
	v_cvt_pk_bf16_f32 v61, v64, v65
	v_add_f32_e32 v244, v244, v245
	v_add_f32_e32 v246, v246, v247
	v_add_f32_e32 v244, v244, v246
	v_fma_f32 v231, v231, v232, v244
	v_lshrrev_b32_e32 v249, v229, v200
	s_waitcnt lgkmcnt(13)
	v_mfma_f32_32x32x16_bf16 v[16:31], v[158:161], v[34:37], v[16:31]
	ds_read_b128 v[122:125], v223 offset:20480
	v_lshrrev_b32_e32 v250, v229, v201
	v_bfe_i32 v235, v249, 0, 1
	v_bfe_i32 v236, v250, 0, 1
	v_bfe_i32 v237, v249, 1, 1
	v_bfe_i32 v238, v250, 1, 1
	v_bfe_i32 v239, v249, 2, 1
	v_bfe_i32 v240, v250, 2, 1
	v_bfe_i32 v241, v249, 3, 1
	v_bfe_i32 v242, v250, 3, 1
	v_bitop3_b32 v70, v70, s33, v235 bitop3:0xe4
	v_bitop3_b32 v86, v86, s33, v236 bitop3:0xe4
	v_bitop3_b32 v71, v71, s33, v237 bitop3:0xe4
	s_waitcnt lgkmcnt(12)
	v_mfma_f32_32x32x16_bf16 v[0:15], v[162:165], v[42:45], v[0:15]
	ds_read_b128 v[126:129], v224 offset:16384
	v_bitop3_b32 v87, v87, s33, v238 bitop3:0xe4
	v_bitop3_b32 v72, v72, s33, v239 bitop3:0xe4
	v_bitop3_b32 v88, v88, s33, v240 bitop3:0xe4
	v_bitop3_b32 v73, v73, s33, v241 bitop3:0xe4
	v_bitop3_b32 v89, v89, s33, v242 bitop3:0xe4
	v_max3_f32 v243, v70, s33, v86
	v_max3_f32 v248, v71, s33, v87
	v_max3_f32 v243, v243, v72, v88
	v_max3_f32 v248, v248, v73, v89
	v_bfe_i32 v235, v249, 8, 1
	v_bfe_i32 v236, v250, 8, 1
	v_bfe_i32 v237, v249, 9, 1
	s_waitcnt lgkmcnt(11)
	v_mfma_f32_32x32x16_bf16 v[16:31], v[166:169], v[42:45], v[16:31]
	ds_read_b128 v[130:133], v224 offset:20480
	v_bfe_i32 v238, v250, 9, 1
	v_bfe_i32 v239, v249, 10, 1
	v_bfe_i32 v240, v250, 10, 1
	v_bfe_i32 v241, v249, 11, 1
	v_bfe_i32 v242, v250, 11, 1
	v_bitop3_b32 v74, v74, s33, v235 bitop3:0xe4
	v_bitop3_b32 v90, v90, s33, v236 bitop3:0xe4
	v_bitop3_b32 v75, v75, s33, v237 bitop3:0xe4
	v_bitop3_b32 v91, v91, s33, v238 bitop3:0xe4
	v_bitop3_b32 v76, v76, s33, v239 bitop3:0xe4
	v_bitop3_b32 v92, v92, s33, v240 bitop3:0xe4
	v_bitop3_b32 v77, v77, s33, v241 bitop3:0xe4
	s_waitcnt lgkmcnt(10)
	v_mfma_f32_32x32x16_bf16 v[0:15], v[170:173], v[50:53], v[0:15]
	ds_read_b128 v[134:137], v225 offset:16384
	v_bitop3_b32 v93, v93, s33, v242 bitop3:0xe4
	v_max3_f32 v243, v243, v74, v90
	v_max3_f32 v248, v248, v75, v91
	v_max3_f32 v243, v243, v76, v92
	v_max3_f32 v248, v248, v77, v93
	v_bfe_i32 v235, v249, 16, 1
	v_bfe_i32 v236, v250, 16, 1
	v_bfe_i32 v237, v249, 17, 1
	v_bfe_i32 v238, v250, 17, 1
	v_bfe_i32 v239, v249, 18, 1
	v_bfe_i32 v240, v250, 18, 1
	v_bfe_i32 v241, v249, 19, 1
	s_waitcnt lgkmcnt(9)
	v_mfma_f32_32x32x16_bf16 v[16:31], v[174:177], v[50:53], v[16:31]
	ds_read_b128 v[138:141], v225 offset:20480
	v_bfe_i32 v242, v250, 19, 1
	v_bitop3_b32 v78, v78, s33, v235 bitop3:0xe4
	v_bitop3_b32 v94, v94, s33, v236 bitop3:0xe4
	v_bitop3_b32 v79, v79, s33, v237 bitop3:0xe4
	v_bitop3_b32 v95, v95, s33, v238 bitop3:0xe4
	v_bitop3_b32 v80, v80, s33, v239 bitop3:0xe4
	v_bitop3_b32 v96, v96, s33, v240 bitop3:0xe4
	v_bitop3_b32 v81, v81, s33, v241 bitop3:0xe4
	v_bitop3_b32 v97, v97, s33, v242 bitop3:0xe4
	v_max3_f32 v243, v243, v78, v94
	v_max3_f32 v248, v248, v79, v95
	v_max3_f32 v243, v243, v80, v96
	s_waitcnt lgkmcnt(8)
	v_mfma_f32_32x32x16_bf16 v[0:15], v[178:181], v[58:61], v[0:15]
	ds_read_b128 v[142:145], v226 offset:16384
	v_max3_f32 v248, v248, v81, v97
	v_bfe_i32 v235, v249, 24, 1
	v_bfe_i32 v236, v250, 24, 1
	v_bfe_i32 v237, v249, 25, 1
	v_bfe_i32 v238, v250, 25, 1
	v_bfe_i32 v239, v249, 26, 1
	v_bfe_i32 v240, v250, 26, 1
	v_bfe_i32 v241, v249, 27, 1
	v_bfe_i32 v242, v250, 27, 1
	v_bitop3_b32 v82, v82, s33, v235 bitop3:0xe4
	v_bitop3_b32 v98, v98, s33, v236 bitop3:0xe4
	v_bitop3_b32 v83, v83, s33, v237 bitop3:0xe4
	s_waitcnt lgkmcnt(7)
	v_mfma_f32_32x32x16_bf16 v[16:31], v[182:185], v[58:61], v[16:31]
	ds_read_b128 v[146:149], v226 offset:20480
	v_bitop3_b32 v99, v99, s33, v238 bitop3:0xe4
	v_bitop3_b32 v84, v84, s33, v239 bitop3:0xe4
	v_bitop3_b32 v100, v100, s33, v240 bitop3:0xe4
	v_bitop3_b32 v85, v85, s33, v241 bitop3:0xe4
	v_bitop3_b32 v101, v101, s33, v242 bitop3:0xe4
	v_max3_f32 v243, v243, v82, v98
	v_max3_f32 v248, v248, v83, v99
	v_max3_f32 v243, v243, v84, v100
	v_max3_f32 v248, v248, v85, v101
	v_max_f32_e32 v243, v243, v248
	v_mov_b32_e32 v248, v243
	s_nop 1
	v_permlane32_swap_b32_e32 v243, v248
	v_max3_f32 v243, v230, v243, v248
	v_cmp_neq_f32_e32 vcc, s33, v243
	s_nop 1
	v_cndmask_b32_e32 v248, 0, v243, vcc
	v_sub_f32_e32 v33, v230, v248
	v_mul_f32_e32 v33, 0x3e38aa3b, v33
	v_exp_f32_e32 v232, v33
	v_mul_f32_e32 v234, 0xbe38aa3b, v248
	v_mov_b32_e32 v230, v243
	s_waitcnt vmcnt(3)
	s_barrier
	s_add_u32 s8, s8, 1
	s_cmp_lt_u32 s8, s9
	s_cbranch_scc1 .Lat_loop_1
	s_branch .Lat_epilogue

.Lat_nors_l0:
	v_pk_fma_f32 v[34:35], v[34:35], v[206:207], v[234:235] op_sel_hi:[1,0,0]
	v_pk_fma_f32 v[36:37], v[36:37], v[206:207], v[234:235] op_sel_hi:[1,0,0]
	v_pk_fma_f32 v[38:39], v[38:39], v[206:207], v[234:235] op_sel_hi:[1,0,0]
	ds_read_b64_tr_b16 v[168:169], v228 offset:3072
	s_waitcnt lgkmcnt(14)
	v_pk_fma_f32 v[40:41], v[40:41], v[206:207], v[234:235] op_sel_hi:[1,0,0]
	v_exp_f32_e32 v34, v34
	v_exp_f32_e32 v35, v35
	ds_read_b64_tr_b16 v[170:171], v227 offset:4096
	s_waitcnt lgkmcnt(14)
	v_exp_f32_e32 v36, v36
	v_exp_f32_e32 v37, v37
	v_exp_f32_e32 v38, v38
	ds_read_b64_tr_b16 v[172:173], v227 offset:5120
	s_waitcnt lgkmcnt(14)
	v_exp_f32_e32 v39, v39
	v_exp_f32_e32 v40, v40
	v_exp_f32_e32 v41, v41
	ds_read_b64_tr_b16 v[174:175], v228 offset:4096
	s_waitcnt lgkmcnt(14)
	v_pk_add_f32 v[244:245], v[34:35], v[38:39]
	v_pk_add_f32 v[246:247], v[36:37], v[40:41]
	v_cvt_pk_bf16_f32 v34, v34, v35
	ds_read_b64_tr_b16 v[176:177], v228 offset:5120
	s_waitcnt lgkmcnt(14)
	v_cvt_pk_bf16_f32 v35, v36, v37
	v_cvt_pk_bf16_f32 v36, v38, v39
	v_cvt_pk_bf16_f32 v37, v40, v41
	ds_read_b64_tr_b16 v[178:179], v227 offset:6144
	s_waitcnt lgkmcnt(14)
	s_waitcnt lgkmcnt(11)
	v_mfma_f32_32x32x16_bf16 v[0:15], v[154:157], v[34:37], v[0:15]
	s_waitcnt lgkmcnt(9)
	v_mfma_f32_32x32x16_bf16 v[16:31], v[158:161], v[34:37], v[16:31]
	v_pk_fma_f32 v[42:43], v[42:43], v[206:207], v[234:235] op_sel_hi:[1,0,0]
	v_pk_fma_f32 v[44:45], v[44:45], v[206:207], v[234:235] op_sel_hi:[1,0,0]
	v_pk_fma_f32 v[46:47], v[46:47], v[206:207], v[234:235] op_sel_hi:[1,0,0]
	ds_read_b64_tr_b16 v[180:181], v227 offset:7168
	v_pk_fma_f32 v[48:49], v[48:49], v[206:207], v[234:235] op_sel_hi:[1,0,0]
	v_exp_f32_e32 v42, v42
	v_exp_f32_e32 v43, v43
	ds_read_b64_tr_b16 v[182:183], v228 offset:6144
	v_exp_f32_e32 v44, v44
	v_exp_f32_e32 v45, v45
	v_exp_f32_e32 v46, v46
	ds_read_b64_tr_b16 v[184:185], v228 offset:7168
	v_exp_f32_e32 v47, v47
	v_exp_f32_e32 v48, v48
	v_exp_f32_e32 v49, v49
	v_pk_add_f32 v[244:245], v[244:245], v[42:43]
	v_pk_add_f32 v[246:247], v[246:247], v[44:45]
	v_pk_add_f32 v[244:245], v[244:245], v[46:47]
	v_pk_add_f32 v[246:247], v[246:247], v[48:49]
	v_cvt_pk_bf16_f32 v42, v42, v43
	v_cvt_pk_bf16_f32 v43, v44, v45
	v_cvt_pk_bf16_f32 v44, v46, v47
	v_cvt_pk_bf16_f32 v45, v48, v49
	s_waitcnt lgkmcnt(10)
	v_mfma_f32_32x32x16_bf16 v[0:15], v[162:165], v[42:45], v[0:15]
	s_waitcnt lgkmcnt(8)
	v_mfma_f32_32x32x16_bf16 v[16:31], v[166:169], v[42:45], v[16:31]
	v_pk_fma_f32 v[50:51], v[50:51], v[206:207], v[234:235] op_sel_hi:[1,0,0]
	v_pk_fma_f32 v[52:53], v[52:53], v[206:207], v[234:235] op_sel_hi:[1,0,0]
	v_pk_fma_f32 v[54:55], v[54:55], v[206:207], v[234:235] op_sel_hi:[1,0,0]
	v_pk_fma_f32 v[56:57], v[56:57], v[206:207], v[234:235] op_sel_hi:[1,0,0]
	v_exp_f32_e32 v50, v50
	v_exp_f32_e32 v51, v51
	v_exp_f32_e32 v52, v52
	v_exp_f32_e32 v53, v53
	v_exp_f32_e32 v54, v54
	v_exp_f32_e32 v55, v55
	v_exp_f32_e32 v56, v56
	v_exp_f32_e32 v57, v57
	v_pk_add_f32 v[244:245], v[244:245], v[50:51]
	v_pk_add_f32 v[246:247], v[246:247], v[52:53]
	v_pk_add_f32 v[244:245], v[244:245], v[54:55]
	v_pk_add_f32 v[246:247], v[246:247], v[56:57]
	v_cvt_pk_bf16_f32 v50, v50, v51
	v_cvt_pk_bf16_f32 v51, v52, v53
	v_cvt_pk_bf16_f32 v52, v54, v55
	v_cvt_pk_bf16_f32 v53, v56, v57
	s_waitcnt lgkmcnt(6)
	v_mfma_f32_32x32x16_bf16 v[0:15], v[170:173], v[50:53], v[0:15]
	s_waitcnt lgkmcnt(4)
	v_mfma_f32_32x32x16_bf16 v[16:31], v[174:177], v[50:53], v[16:31]
	v_pk_fma_f32 v[58:59], v[58:59], v[206:207], v[234:235] op_sel_hi:[1,0,0]
	v_pk_fma_f32 v[60:61], v[60:61], v[206:207], v[234:235] op_sel_hi:[1,0,0]
	v_pk_fma_f32 v[62:63], v[62:63], v[206:207], v[234:235] op_sel_hi:[1,0,0]
	v_pk_fma_f32 v[64:65], v[64:65], v[206:207], v[234:235] op_sel_hi:[1,0,0]
	v_exp_f32_e32 v58, v58
	v_exp_f32_e32 v59, v59
	v_exp_f32_e32 v60, v60
	v_exp_f32_e32 v61, v61
	v_exp_f32_e32 v62, v62
	v_exp_f32_e32 v63, v63
	v_exp_f32_e32 v64, v64
	v_exp_f32_e32 v65, v65
	v_pk_add_f32 v[244:245], v[244:245], v[58:59]
	v_pk_add_f32 v[246:247], v[246:247], v[60:61]
	v_pk_add_f32 v[244:245], v[244:245], v[62:63]
	v_pk_add_f32 v[246:247], v[246:247], v[64:65]
	v_cvt_pk_bf16_f32 v58, v58, v59
	v_cvt_pk_bf16_f32 v59, v60, v61
	v_cvt_pk_bf16_f32 v60, v62, v63
	v_cvt_pk_bf16_f32 v61, v64, v65
	v_add_f32_e32 v244, v244, v245
	v_add_f32_e32 v246, v246, v247
	v_add_f32_e32 v244, v244, v246
	v_fma_f32 v231, v231, v232, v244
	s_waitcnt lgkmcnt(2)
	v_mfma_f32_32x32x16_bf16 v[0:15], v[178:181], v[58:61], v[0:15]
	s_waitcnt lgkmcnt(0)
	v_mfma_f32_32x32x16_bf16 v[16:31], v[182:185], v[58:61], v[16:31]
	s_waitcnt vmcnt(3)
	s_barrier
	s_add_u32 s8, s8, 1
	s_cmp_lt_u32 s8, s9
	s_cbranch_scc1 .Lat_loop_1
	s_branch .Lat_epilogue

.Lat_nors_f1:
	v_pk_fma_f32 v[70:71], v[70:71], v[206:207], v[234:235] op_sel_hi:[1,0,0]
	v_pk_fma_f32 v[72:73], v[72:73], v[206:207], v[234:235] op_sel_hi:[1,0,0]
	s_waitcnt lgkmcnt(7)
	v_mfma_f32_32x32x16_bf16 v[34:49], v[118:121], v[102:105], 0
	ds_read_b64_tr_b16 v[154:155], v227 offset:8192
	ds_read_b64_tr_b16 v[156:157], v227 offset:9216
	v_pk_fma_f32 v[74:75], v[74:75], v[206:207], v[234:235] op_sel_hi:[1,0,0]
	v_pk_fma_f32 v[76:77], v[76:77], v[206:207], v[234:235] op_sel_hi:[1,0,0]
	v_exp_f32_e32 v70, v70
	v_exp_f32_e32 v71, v71
	v_exp_f32_e32 v72, v72
	v_exp_f32_e32 v73, v73
	v_exp_f32_e32 v74, v74
	v_exp_f32_e32 v75, v75
	s_waitcnt lgkmcnt(8)
	v_mfma_f32_32x32x16_bf16 v[50:65], v[122:125], v[102:105], 0
	ds_read_b64_tr_b16 v[158:159], v228 offset:8192
	ds_read_b64_tr_b16 v[160:161], v228 offset:9216
	v_exp_f32_e32 v76, v76
	v_exp_f32_e32 v77, v77
	v_pk_add_f32 v[244:245], v[70:71], v[74:75]
	v_pk_add_f32 v[246:247], v[72:73], v[76:77]
	v_cvt_pk_bf16_f32 v70, v70, v71
	v_cvt_pk_bf16_f32 v71, v72, v73
	v_cvt_pk_bf16_f32 v72, v74, v75
	v_cvt_pk_bf16_f32 v73, v76, v77
	v_pk_fma_f32 v[78:79], v[78:79], v[206:207], v[234:235] op_sel_hi:[1,0,0]
	s_waitcnt lgkmcnt(9)
	v_mfma_f32_32x32x16_bf16 v[34:49], v[126:129], v[106:109], v[34:49]
	ds_read_b64_tr_b16 v[162:163], v227 offset:10240
	ds_read_b64_tr_b16 v[164:165], v227 offset:11264
	v_pk_fma_f32 v[80:81], v[80:81], v[206:207], v[234:235] op_sel_hi:[1,0,0]
	v_pk_fma_f32 v[82:83], v[82:83], v[206:207], v[234:235] op_sel_hi:[1,0,0]
	v_pk_fma_f32 v[84:85], v[84:85], v[206:207], v[234:235] op_sel_hi:[1,0,0]
	v_exp_f32_e32 v78, v78
	v_exp_f32_e32 v79, v79
	v_exp_f32_e32 v80, v80
	v_exp_f32_e32 v81, v81
	v_exp_f32_e32 v82, v82
	v_exp_f32_e32 v83, v83
	s_waitcnt lgkmcnt(10)
	v_mfma_f32_32x32x16_bf16 v[50:65], v[130:133], v[106:109], v[50:65]
	ds_read_b64_tr_b16 v[166:167], v228 offset:10240
	ds_read_b64_tr_b16 v[168:169], v228 offset:11264
	v_exp_f32_e32 v84, v84
	v_exp_f32_e32 v85, v85
	v_pk_add_f32 v[244:245], v[244:245], v[78:79]
	v_pk_add_f32 v[246:247], v[246:247], v[80:81]
	v_pk_add_f32 v[244:245], v[244:245], v[82:83]
	v_pk_add_f32 v[246:247], v[246:247], v[84:85]
	v_cvt_pk_bf16_f32 v78, v78, v79
	v_cvt_pk_bf16_f32 v79, v80, v81
	v_cvt_pk_bf16_f32 v80, v82, v83
	s_waitcnt lgkmcnt(11)
	v_mfma_f32_32x32x16_bf16 v[34:49], v[134:137], v[110:113], v[34:49]
	ds_read_b64_tr_b16 v[170:171], v227 offset:12288
	ds_read_b64_tr_b16 v[172:173], v227 offset:13312
	v_cvt_pk_bf16_f32 v81, v84, v85
	v_pk_fma_f32 v[86:87], v[86:87], v[206:207], v[234:235] op_sel_hi:[1,0,0]
	v_pk_fma_f32 v[88:89], v[88:89], v[206:207], v[234:235] op_sel_hi:[1,0,0]
	v_pk_fma_f32 v[90:91], v[90:91], v[206:207], v[234:235] op_sel_hi:[1,0,0]
	v_pk_fma_f32 v[92:93], v[92:93], v[206:207], v[234:235] op_sel_hi:[1,0,0]
	v_exp_f32_e32 v86, v86
	v_exp_f32_e32 v87, v87
	v_exp_f32_e32 v88, v88
	v_exp_f32_e32 v89, v89
	s_waitcnt lgkmcnt(12)
	v_mfma_f32_32x32x16_bf16 v[50:65], v[138:141], v[110:113], v[50:65]
	ds_read_b64_tr_b16 v[174:175], v228 offset:12288
	ds_read_b64_tr_b16 v[176:177], v228 offset:13312
	v_exp_f32_e32 v90, v90
	v_exp_f32_e32 v91, v91
	v_exp_f32_e32 v92, v92
	v_exp_f32_e32 v93, v93
	v_pk_add_f32 v[244:245], v[244:245], v[86:87]
	v_pk_add_f32 v[246:247], v[246:247], v[88:89]
	v_pk_add_f32 v[244:245], v[244:245], v[90:91]
	v_pk_add_f32 v[246:247], v[246:247], v[92:93]
	v_cvt_pk_bf16_f32 v86, v86, v87
	s_waitcnt lgkmcnt(13)
	v_mfma_f32_32x32x16_bf16 v[34:49], v[142:145], v[114:117], v[34:49]
	ds_read_b64_tr_b16 v[178:179], v227 offset:14336
	ds_read_b64_tr_b16 v[180:181], v227 offset:15360
	v_cvt_pk_bf16_f32 v87, v88, v89
	v_cvt_pk_bf16_f32 v88, v90, v91
	v_cvt_pk_bf16_f32 v89, v92, v93
	v_pk_fma_f32 v[94:95], v[94:95], v[206:207], v[234:235] op_sel_hi:[1,0,0]
	v_pk_fma_f32 v[96:97], v[96:97], v[206:207], v[234:235] op_sel_hi:[1,0,0]
	v_pk_fma_f32 v[98:99], v[98:99], v[206:207], v[234:235] op_sel_hi:[1,0,0]
	v_pk_fma_f32 v[100:101], v[100:101], v[206:207], v[234:235] op_sel_hi:[1,0,0]
	v_exp_f32_e32 v94, v94
	v_exp_f32_e32 v95, v95
	s_waitcnt lgkmcnt(14)
	v_mfma_f32_32x32x16_bf16 v[50:65], v[146:149], v[114:117], v[50:65]
	ds_read_b64_tr_b16 v[182:183], v228 offset:14336
	ds_read_b64_tr_b16 v[184:185], v228 offset:15360
	s_waitcnt lgkmcnt(14)
	v_exp_f32_e32 v96, v96
	v_exp_f32_e32 v97, v97
	v_exp_f32_e32 v98, v98
	v_exp_f32_e32 v99, v99
	v_exp_f32_e32 v100, v100
	v_exp_f32_e32 v101, v101
	v_pk_add_f32 v[244:245], v[244:245], v[94:95]
	v_pk_add_f32 v[246:247], v[246:247], v[96:97]
	s_waitcnt lgkmcnt(14)
	v_mfma_f32_32x32x16_bf16 v[0:15], v[154:157], v[70:73], v[0:15]
	ds_read_b128 v[118:121], v223 offset:24576
	v_pk_add_f32 v[244:245], v[244:245], v[98:99]
	v_pk_add_f32 v[246:247], v[246:247], v[100:101]
	v_cvt_pk_bf16_f32 v94, v94, v95
	v_cvt_pk_bf16_f32 v95, v96, v97
	v_cvt_pk_bf16_f32 v96, v98, v99
	v_cvt_pk_bf16_f32 v97, v100, v101
	v_add_f32_e32 v244, v244, v245
	v_add_f32_e32 v246, v246, v247
	v_add_f32_e32 v244, v244, v246
	v_fma_f32 v231, v231, v232, v244
	s_waitcnt vmcnt(4)
	v_lshrrev_b32_e32 v249, v229, v202
	s_waitcnt lgkmcnt(13)
	v_mfma_f32_32x32x16_bf16 v[16:31], v[158:161], v[70:73], v[16:31]
	ds_read_b128 v[122:125], v223 offset:28672
	v_lshrrev_b32_e32 v250, v229, v203
	v_bfe_i32 v235, v249, 0, 1
	v_bfe_i32 v236, v250, 0, 1
	v_bfe_i32 v237, v249, 1, 1
	v_bfe_i32 v238, v250, 1, 1
	v_bfe_i32 v239, v249, 2, 1
	v_bfe_i32 v240, v250, 2, 1
	v_bfe_i32 v241, v249, 3, 1
	v_bfe_i32 v242, v250, 3, 1
	v_bitop3_b32 v34, v34, s33, v235 bitop3:0xe4
	v_bitop3_b32 v50, v50, s33, v236 bitop3:0xe4
	v_bitop3_b32 v35, v35, s33, v237 bitop3:0xe4
	s_waitcnt lgkmcnt(12)
	v_mfma_f32_32x32x16_bf16 v[0:15], v[162:165], v[78:81], v[0:15]
	ds_read_b128 v[126:129], v224 offset:24576
	v_bitop3_b32 v51, v51, s33, v238 bitop3:0xe4
	v_bitop3_b32 v36, v36, s33, v239 bitop3:0xe4
	v_bitop3_b32 v52, v52, s33, v240 bitop3:0xe4
	v_bitop3_b32 v37, v37, s33, v241 bitop3:0xe4
	v_bitop3_b32 v53, v53, s33, v242 bitop3:0xe4
	v_max3_f32 v243, v34, s33, v50
	v_max3_f32 v248, v35, s33, v51
	v_max3_f32 v243, v243, v36, v52
	v_max3_f32 v248, v248, v37, v53
	v_bfe_i32 v235, v249, 8, 1
	v_bfe_i32 v236, v250, 8, 1
	v_bfe_i32 v237, v249, 9, 1
	s_waitcnt lgkmcnt(11)
	v_mfma_f32_32x32x16_bf16 v[16:31], v[166:169], v[78:81], v[16:31]
	ds_read_b128 v[130:133], v224 offset:28672
	v_bfe_i32 v238, v250, 9, 1
	v_bfe_i32 v239, v249, 10, 1
	v_bfe_i32 v240, v250, 10, 1
	v_bfe_i32 v241, v249, 11, 1
	v_bfe_i32 v242, v250, 11, 1
	v_bitop3_b32 v38, v38, s33, v235 bitop3:0xe4
	v_bitop3_b32 v54, v54, s33, v236 bitop3:0xe4
	v_bitop3_b32 v39, v39, s33, v237 bitop3:0xe4
	v_bitop3_b32 v55, v55, s33, v238 bitop3:0xe4
	v_bitop3_b32 v40, v40, s33, v239 bitop3:0xe4
	v_bitop3_b32 v56, v56, s33, v240 bitop3:0xe4
	v_bitop3_b32 v41, v41, s33, v241 bitop3:0xe4
	s_waitcnt lgkmcnt(10)
	v_mfma_f32_32x32x16_bf16 v[0:15], v[170:173], v[86:89], v[0:15]
	ds_read_b128 v[134:137], v225 offset:24576
	v_bitop3_b32 v57, v57, s33, v242 bitop3:0xe4
	v_max3_f32 v243, v243, v38, v54
	v_max3_f32 v248, v248, v39, v55
	v_max3_f32 v243, v243, v40, v56
	v_max3_f32 v248, v248, v41, v57
	v_bfe_i32 v235, v249, 16, 1
	v_bfe_i32 v236, v250, 16, 1
	v_bfe_i32 v237, v249, 17, 1
	v_bfe_i32 v238, v250, 17, 1
	v_bfe_i32 v239, v249, 18, 1
	v_bfe_i32 v240, v250, 18, 1
	v_bfe_i32 v241, v249, 19, 1
	s_waitcnt lgkmcnt(9)
	v_mfma_f32_32x32x16_bf16 v[16:31], v[174:177], v[86:89], v[16:31]
	ds_read_b128 v[138:141], v225 offset:28672
	v_bfe_i32 v242, v250, 19, 1
	v_bitop3_b32 v42, v42, s33, v235 bitop3:0xe4
	v_bitop3_b32 v58, v58, s33, v236 bitop3:0xe4
	v_bitop3_b32 v43, v43, s33, v237 bitop3:0xe4
	v_bitop3_b32 v59, v59, s33, v238 bitop3:0xe4
	v_bitop3_b32 v44, v44, s33, v239 bitop3:0xe4
	v_bitop3_b32 v60, v60, s33, v240 bitop3:0xe4
	v_bitop3_b32 v45, v45, s33, v241 bitop3:0xe4
	v_bitop3_b32 v61, v61, s33, v242 bitop3:0xe4
	v_max3_f32 v243, v243, v42, v58
	v_max3_f32 v248, v248, v43, v59
	v_max3_f32 v243, v243, v44, v60
	s_waitcnt lgkmcnt(8)
	v_mfma_f32_32x32x16_bf16 v[0:15], v[178:181], v[94:97], v[0:15]
	ds_read_b128 v[142:145], v226 offset:24576
	v_max3_f32 v248, v248, v45, v61
	v_bfe_i32 v235, v249, 24, 1
	v_bfe_i32 v236, v250, 24, 1
	v_bfe_i32 v237, v249, 25, 1
	v_bfe_i32 v238, v250, 25, 1
	v_bfe_i32 v239, v249, 26, 1
	v_bfe_i32 v240, v250, 26, 1
	v_bfe_i32 v241, v249, 27, 1
	v_bfe_i32 v242, v250, 27, 1
	v_bitop3_b32 v46, v46, s33, v235 bitop3:0xe4
	v_bitop3_b32 v62, v62, s33, v236 bitop3:0xe4
	v_bitop3_b32 v47, v47, s33, v237 bitop3:0xe4
	s_waitcnt lgkmcnt(7)
	v_mfma_f32_32x32x16_bf16 v[16:31], v[182:185], v[94:97], v[16:31]
	ds_read_b128 v[146:149], v226 offset:28672
	v_bitop3_b32 v63, v63, s33, v238 bitop3:0xe4
	v_bitop3_b32 v48, v48, s33, v239 bitop3:0xe4
	v_bitop3_b32 v64, v64, s33, v240 bitop3:0xe4
	v_bitop3_b32 v49, v49, s33, v241 bitop3:0xe4
	v_bitop3_b32 v65, v65, s33, v242 bitop3:0xe4
	v_max3_f32 v243, v243, v46, v62
	v_max3_f32 v248, v248, v47, v63
	v_max3_f32 v243, v243, v48, v64
	v_max3_f32 v248, v248, v49, v65
	v_max_f32_e32 v243, v243, v248
	v_mov_b32_e32 v248, v243
	s_nop 1
	v_permlane32_swap_b32_e32 v243, v248
	v_max3_f32 v243, v230, v243, v248
	v_cmp_neq_f32_e32 vcc, s33, v243
	s_nop 1
	v_cndmask_b32_e32 v248, 0, v243, vcc
	v_sub_f32_e32 v33, v230, v248
	v_mul_f32_e32 v33, 0x3e38aa3b, v33
	v_exp_f32_e32 v232, v33
	v_mul_f32_e32 v234, 0xbe38aa3b, v248
	v_mov_b32_e32 v230, v243
	s_waitcnt vmcnt(2)
	s_barrier
	s_add_u32 s8, s8, 1
	s_cmp_lt_u32 s8, s9
	s_cbranch_scc1 .Lat_loop_2
	s_branch .Lat_epilogue

.Lat_nors_l1:
	v_pk_fma_f32 v[70:71], v[70:71], v[206:207], v[234:235] op_sel_hi:[1,0,0]
	v_pk_fma_f32 v[72:73], v[72:73], v[206:207], v[234:235] op_sel_hi:[1,0,0]
	v_pk_fma_f32 v[74:75], v[74:75], v[206:207], v[234:235] op_sel_hi:[1,0,0]
	ds_read_b64_tr_b16 v[168:169], v228 offset:11264
	s_waitcnt lgkmcnt(14)
	v_pk_fma_f32 v[76:77], v[76:77], v[206:207], v[234:235] op_sel_hi:[1,0,0]
	v_exp_f32_e32 v70, v70
	v_exp_f32_e32 v71, v71
	ds_read_b64_tr_b16 v[170:171], v227 offset:12288
	s_waitcnt lgkmcnt(14)
	v_exp_f32_e32 v72, v72
	v_exp_f32_e32 v73, v73
	v_exp_f32_e32 v74, v74
	ds_read_b64_tr_b16 v[172:173], v227 offset:13312
	s_waitcnt lgkmcnt(14)
	v_exp_f32_e32 v75, v75
	v_exp_f32_e32 v76, v76
	v_exp_f32_e32 v77, v77
	ds_read_b64_tr_b16 v[174:175], v228 offset:12288
	s_waitcnt lgkmcnt(14)
	v_pk_add_f32 v[244:245], v[70:71], v[74:75]
	v_pk_add_f32 v[246:247], v[72:73], v[76:77]
	v_cvt_pk_bf16_f32 v70, v70, v71
	ds_read_b64_tr_b16 v[176:177], v228 offset:13312
	s_waitcnt lgkmcnt(14)
	v_cvt_pk_bf16_f32 v71, v72, v73
	v_cvt_pk_bf16_f32 v72, v74, v75
	v_cvt_pk_bf16_f32 v73, v76, v77
	ds_read_b64_tr_b16 v[178:179], v227 offset:14336
	s_waitcnt lgkmcnt(14)
	s_waitcnt lgkmcnt(11)
	v_mfma_f32_32x32x16_bf16 v[0:15], v[154:157], v[70:73], v[0:15]
	s_waitcnt lgkmcnt(9)
	v_mfma_f32_32x32x16_bf16 v[16:31], v[158:161], v[70:73], v[16:31]
	v_pk_fma_f32 v[78:79], v[78:79], v[206:207], v[234:235] op_sel_hi:[1,0,0]
	v_pk_fma_f32 v[80:81], v[80:81], v[206:207], v[234:235] op_sel_hi:[1,0,0]
	v_pk_fma_f32 v[82:83], v[82:83], v[206:207], v[234:235] op_sel_hi:[1,0,0]
	ds_read_b64_tr_b16 v[180:181], v227 offset:15360
	v_pk_fma_f32 v[84:85], v[84:85], v[206:207], v[234:235] op_sel_hi:[1,0,0]
	v_exp_f32_e32 v78, v78
	v_exp_f32_e32 v79, v79
	ds_read_b64_tr_b16 v[182:183], v228 offset:14336
	v_exp_f32_e32 v80, v80
	v_exp_f32_e32 v81, v81
	v_exp_f32_e32 v82, v82
	ds_read_b64_tr_b16 v[184:185], v228 offset:15360
	v_exp_f32_e32 v83, v83
	v_exp_f32_e32 v84, v84
	v_exp_f32_e32 v85, v85
	v_pk_add_f32 v[244:245], v[244:245], v[78:79]
	v_pk_add_f32 v[246:247], v[246:247], v[80:81]
	v_pk_add_f32 v[244:245], v[244:245], v[82:83]
	v_pk_add_f32 v[246:247], v[246:247], v[84:85]
	v_cvt_pk_bf16_f32 v78, v78, v79
	v_cvt_pk_bf16_f32 v79, v80, v81
	v_cvt_pk_bf16_f32 v80, v82, v83
	v_cvt_pk_bf16_f32 v81, v84, v85
	s_waitcnt lgkmcnt(10)
	v_mfma_f32_32x32x16_bf16 v[0:15], v[162:165], v[78:81], v[0:15]
	s_waitcnt lgkmcnt(8)
	v_mfma_f32_32x32x16_bf16 v[16:31], v[166:169], v[78:81], v[16:31]
	v_pk_fma_f32 v[86:87], v[86:87], v[206:207], v[234:235] op_sel_hi:[1,0,0]
	v_pk_fma_f32 v[88:89], v[88:89], v[206:207], v[234:235] op_sel_hi:[1,0,0]
	v_pk_fma_f32 v[90:91], v[90:91], v[206:207], v[234:235] op_sel_hi:[1,0,0]
	v_pk_fma_f32 v[92:93], v[92:93], v[206:207], v[234:235] op_sel_hi:[1,0,0]
	v_exp_f32_e32 v86, v86
	v_exp_f32_e32 v87, v87
	v_exp_f32_e32 v88, v88
	v_exp_f32_e32 v89, v89
	v_exp_f32_e32 v90, v90
	v_exp_f32_e32 v91, v91
	v_exp_f32_e32 v92, v92
	v_exp_f32_e32 v93, v93
	v_pk_add_f32 v[244:245], v[244:245], v[86:87]
	v_pk_add_f32 v[246:247], v[246:247], v[88:89]
	v_pk_add_f32 v[244:245], v[244:245], v[90:91]
	v_pk_add_f32 v[246:247], v[246:247], v[92:93]
	v_cvt_pk_bf16_f32 v86, v86, v87
	v_cvt_pk_bf16_f32 v87, v88, v89
	v_cvt_pk_bf16_f32 v88, v90, v91
	v_cvt_pk_bf16_f32 v89, v92, v93
	s_waitcnt lgkmcnt(6)
	v_mfma_f32_32x32x16_bf16 v[0:15], v[170:173], v[86:89], v[0:15]
	s_waitcnt lgkmcnt(4)
	v_mfma_f32_32x32x16_bf16 v[16:31], v[174:177], v[86:89], v[16:31]
	v_pk_fma_f32 v[94:95], v[94:95], v[206:207], v[234:235] op_sel_hi:[1,0,0]
	v_pk_fma_f32 v[96:97], v[96:97], v[206:207], v[234:235] op_sel_hi:[1,0,0]
	v_pk_fma_f32 v[98:99], v[98:99], v[206:207], v[234:235] op_sel_hi:[1,0,0]
	v_pk_fma_f32 v[100:101], v[100:101], v[206:207], v[234:235] op_sel_hi:[1,0,0]
	v_exp_f32_e32 v94, v94
	v_exp_f32_e32 v95, v95
	v_exp_f32_e32 v96, v96
	v_exp_f32_e32 v97, v97
	v_exp_f32_e32 v98, v98
	v_exp_f32_e32 v99, v99
	v_exp_f32_e32 v100, v100
	v_exp_f32_e32 v101, v101
	v_pk_add_f32 v[244:245], v[244:245], v[94:95]
	v_pk_add_f32 v[246:247], v[246:247], v[96:97]
	v_pk_add_f32 v[244:245], v[244:245], v[98:99]
	v_pk_add_f32 v[246:247], v[246:247], v[100:101]
	v_cvt_pk_bf16_f32 v94, v94, v95
	v_cvt_pk_bf16_f32 v95, v96, v97
	v_cvt_pk_bf16_f32 v96, v98, v99
	v_cvt_pk_bf16_f32 v97, v100, v101
	v_add_f32_e32 v244, v244, v245
	v_add_f32_e32 v246, v246, v247
	v_add_f32_e32 v244, v244, v246
	v_fma_f32 v231, v231, v232, v244
	s_waitcnt lgkmcnt(2)
	v_mfma_f32_32x32x16_bf16 v[0:15], v[178:181], v[94:97], v[0:15]
	s_waitcnt lgkmcnt(0)
	v_mfma_f32_32x32x16_bf16 v[16:31], v[182:185], v[94:97], v[16:31]
	s_waitcnt vmcnt(2)
	s_barrier
	s_add_u32 s8, s8, 1
	s_cmp_lt_u32 s8, s9
	s_cbranch_scc1 .Lat_loop_2
	s_branch .Lat_epilogue

.Lat_nors_f2:
	v_pk_fma_f32 v[34:35], v[34:35], v[206:207], v[234:235] op_sel_hi:[1,0,0]
	v_pk_fma_f32 v[36:37], v[36:37], v[206:207], v[234:235] op_sel_hi:[1,0,0]
	s_waitcnt lgkmcnt(7)
	v_mfma_f32_32x32x16_bf16 v[70:85], v[118:121], v[102:105], 0
	ds_read_b64_tr_b16 v[154:155], v227 offset:16384
	ds_read_b64_tr_b16 v[156:157], v227 offset:17408
	v_pk_fma_f32 v[38:39], v[38:39], v[206:207], v[234:235] op_sel_hi:[1,0,0]
	v_pk_fma_f32 v[40:41], v[40:41], v[206:207], v[234:235] op_sel_hi:[1,0,0]
	v_exp_f32_e32 v34, v34
	v_exp_f32_e32 v35, v35
	v_exp_f32_e32 v36, v36
	v_exp_f32_e32 v37, v37
	v_exp_f32_e32 v38, v38
	v_exp_f32_e32 v39, v39
	s_waitcnt lgkmcnt(8)
	v_mfma_f32_32x32x16_bf16 v[86:101], v[122:125], v[102:105], 0
	ds_read_b64_tr_b16 v[158:159], v228 offset:16384
	ds_read_b64_tr_b16 v[160:161], v228 offset:17408
	v_exp_f32_e32 v40, v40
	v_exp_f32_e32 v41, v41
	v_pk_add_f32 v[244:245], v[34:35], v[38:39]
	v_pk_add_f32 v[246:247], v[36:37], v[40:41]
	v_cvt_pk_bf16_f32 v34, v34, v35
	v_cvt_pk_bf16_f32 v35, v36, v37
	v_cvt_pk_bf16_f32 v36, v38, v39
	v_cvt_pk_bf16_f32 v37, v40, v41
	v_pk_fma_f32 v[42:43], v[42:43], v[206:207], v[234:235] op_sel_hi:[1,0,0]
	s_waitcnt lgkmcnt(9)
	v_mfma_f32_32x32x16_bf16 v[70:85], v[126:129], v[106:109], v[70:85]
	ds_read_b64_tr_b16 v[162:163], v227 offset:18432
	ds_read_b64_tr_b16 v[164:165], v227 offset:19456
	v_pk_fma_f32 v[44:45], v[44:45], v[206:207], v[234:235] op_sel_hi:[1,0,0]
	v_pk_fma_f32 v[46:47], v[46:47], v[206:207], v[234:235] op_sel_hi:[1,0,0]
	v_pk_fma_f32 v[48:49], v[48:49], v[206:207], v[234:235] op_sel_hi:[1,0,0]
	v_exp_f32_e32 v42, v42
	v_exp_f32_e32 v43, v43
	v_exp_f32_e32 v44, v44
	v_exp_f32_e32 v45, v45
	v_exp_f32_e32 v46, v46
	v_exp_f32_e32 v47, v47
	s_waitcnt lgkmcnt(10)
	v_mfma_f32_32x32x16_bf16 v[86:101], v[130:133], v[106:109], v[86:101]
	ds_read_b64_tr_b16 v[166:167], v228 offset:18432
	ds_read_b64_tr_b16 v[168:169], v228 offset:19456
	v_exp_f32_e32 v48, v48
	v_exp_f32_e32 v49, v49
	v_pk_add_f32 v[244:245], v[244:245], v[42:43]
	v_pk_add_f32 v[246:247], v[246:247], v[44:45]
	v_pk_add_f32 v[244:245], v[244:245], v[46:47]
	v_pk_add_f32 v[246:247], v[246:247], v[48:49]
	v_cvt_pk_bf16_f32 v42, v42, v43
	v_cvt_pk_bf16_f32 v43, v44, v45
	v_cvt_pk_bf16_f32 v44, v46, v47
	s_waitcnt lgkmcnt(11)
	v_mfma_f32_32x32x16_bf16 v[70:85], v[134:137], v[110:113], v[70:85]
	ds_read_b64_tr_b16 v[170:171], v227 offset:20480
	ds_read_b64_tr_b16 v[172:173], v227 offset:21504
	v_cvt_pk_bf16_f32 v45, v48, v49
	v_pk_fma_f32 v[50:51], v[50:51], v[206:207], v[234:235] op_sel_hi:[1,0,0]
	v_pk_fma_f32 v[52:53], v[52:53], v[206:207], v[234:235] op_sel_hi:[1,0,0]
	v_pk_fma_f32 v[54:55], v[54:55], v[206:207], v[234:235] op_sel_hi:[1,0,0]
	v_pk_fma_f32 v[56:57], v[56:57], v[206:207], v[234:235] op_sel_hi:[1,0,0]
	v_exp_f32_e32 v50, v50
	v_exp_f32_e32 v51, v51
	v_exp_f32_e32 v52, v52
	v_exp_f32_e32 v53, v53
	s_waitcnt lgkmcnt(12)
	v_mfma_f32_32x32x16_bf16 v[86:101], v[138:141], v[110:113], v[86:101]
	ds_read_b64_tr_b16 v[174:175], v228 offset:20480
	ds_read_b64_tr_b16 v[176:177], v228 offset:21504
	v_exp_f32_e32 v54, v54
	v_exp_f32_e32 v55, v55
	v_exp_f32_e32 v56, v56
	v_exp_f32_e32 v57, v57
	v_pk_add_f32 v[244:245], v[244:245], v[50:51]
	v_pk_add_f32 v[246:247], v[246:247], v[52:53]
	v_pk_add_f32 v[244:245], v[244:245], v[54:55]
	v_pk_add_f32 v[246:247], v[246:247], v[56:57]
	v_cvt_pk_bf16_f32 v50, v50, v51
	s_waitcnt lgkmcnt(13)
	v_mfma_f32_32x32x16_bf16 v[70:85], v[142:145], v[114:117], v[70:85]
	ds_read_b64_tr_b16 v[178:179], v227 offset:22528
	ds_read_b64_tr_b16 v[180:181], v227 offset:23552
	v_cvt_pk_bf16_f32 v51, v52, v53
	v_cvt_pk_bf16_f32 v52, v54, v55
	v_cvt_pk_bf16_f32 v53, v56, v57
	v_pk_fma_f32 v[58:59], v[58:59], v[206:207], v[234:235] op_sel_hi:[1,0,0]
	v_pk_fma_f32 v[60:61], v[60:61], v[206:207], v[234:235] op_sel_hi:[1,0,0]
	v_pk_fma_f32 v[62:63], v[62:63], v[206:207], v[234:235] op_sel_hi:[1,0,0]
	v_pk_fma_f32 v[64:65], v[64:65], v[206:207], v[234:235] op_sel_hi:[1,0,0]
	v_exp_f32_e32 v58, v58
	v_exp_f32_e32 v59, v59
	s_waitcnt lgkmcnt(14)
	v_mfma_f32_32x32x16_bf16 v[86:101], v[146:149], v[114:117], v[86:101]
	ds_read_b64_tr_b16 v[182:183], v228 offset:22528
	ds_read_b64_tr_b16 v[184:185], v228 offset:23552
	s_waitcnt lgkmcnt(14)
	v_exp_f32_e32 v60, v60
	v_exp_f32_e32 v61, v61
	v_exp_f32_e32 v62, v62
	v_exp_f32_e32 v63, v63
	v_exp_f32_e32 v64, v64
	v_exp_f32_e32 v65, v65
	v_pk_add_f32 v[244:245], v[244:245], v[58:59]
	v_pk_add_f32 v[246:247], v[246:247], v[60:61]
	s_waitcnt lgkmcnt(14)
	v_mfma_f32_32x32x16_bf16 v[0:15], v[154:157], v[34:37], v[0:15]
	ds_read_b128 v[118:121], v223 offset:0
	v_pk_add_f32 v[244:245], v[244:245], v[62:63]
	v_pk_add_f32 v[246:247], v[246:247], v[64:65]
	v_cvt_pk_bf16_f32 v58, v58, v59
	v_cvt_pk_bf16_f32 v59, v60, v61
	v_cvt_pk_bf16_f32 v60, v62, v63
	v_cvt_pk_bf16_f32 v61, v64, v65
	v_add_f32_e32 v244, v244, v245
	v_add_f32_e32 v246, v246, v247
	v_add_f32_e32 v244, v244, v246
	v_fma_f32 v231, v231, v232, v244
	v_lshrrev_b32_e32 v249, v229, v204
	s_waitcnt lgkmcnt(13)
	v_mfma_f32_32x32x16_bf16 v[16:31], v[158:161], v[34:37], v[16:31]
	ds_read_b128 v[122:125], v223 offset:4096
	v_lshrrev_b32_e32 v250, v229, v205
	v_bfe_i32 v235, v249, 0, 1
	v_bfe_i32 v236, v250, 0, 1
	v_bfe_i32 v237, v249, 1, 1
	v_bfe_i32 v238, v250, 1, 1
	v_bfe_i32 v239, v249, 2, 1
	v_bfe_i32 v240, v250, 2, 1
	v_bfe_i32 v241, v249, 3, 1
	v_bfe_i32 v242, v250, 3, 1
	v_bitop3_b32 v70, v70, s33, v235 bitop3:0xe4
	v_bitop3_b32 v86, v86, s33, v236 bitop3:0xe4
	v_bitop3_b32 v71, v71, s33, v237 bitop3:0xe4
	s_waitcnt lgkmcnt(12)
	v_mfma_f32_32x32x16_bf16 v[0:15], v[162:165], v[42:45], v[0:15]
	ds_read_b128 v[126:129], v224 offset:0
	v_bitop3_b32 v87, v87, s33, v238 bitop3:0xe4
	v_bitop3_b32 v72, v72, s33, v239 bitop3:0xe4
	v_bitop3_b32 v88, v88, s33, v240 bitop3:0xe4
	v_bitop3_b32 v73, v73, s33, v241 bitop3:0xe4
	v_bitop3_b32 v89, v89, s33, v242 bitop3:0xe4
	v_max3_f32 v243, v70, s33, v86
	v_max3_f32 v248, v71, s33, v87
	v_max3_f32 v243, v243, v72, v88
	v_max3_f32 v248, v248, v73, v89
	v_bfe_i32 v235, v249, 8, 1
	v_bfe_i32 v236, v250, 8, 1
	v_bfe_i32 v237, v249, 9, 1
	s_waitcnt lgkmcnt(11)
	v_mfma_f32_32x32x16_bf16 v[16:31], v[166:169], v[42:45], v[16:31]
	ds_read_b128 v[130:133], v224 offset:4096
	v_bfe_i32 v238, v250, 9, 1
	v_bfe_i32 v239, v249, 10, 1
	v_bfe_i32 v240, v250, 10, 1
	v_bfe_i32 v241, v249, 11, 1
	v_bfe_i32 v242, v250, 11, 1
	v_bitop3_b32 v74, v74, s33, v235 bitop3:0xe4
	v_bitop3_b32 v90, v90, s33, v236 bitop3:0xe4
	v_bitop3_b32 v75, v75, s33, v237 bitop3:0xe4
	v_bitop3_b32 v91, v91, s33, v238 bitop3:0xe4
	v_bitop3_b32 v76, v76, s33, v239 bitop3:0xe4
	v_bitop3_b32 v92, v92, s33, v240 bitop3:0xe4
	v_bitop3_b32 v77, v77, s33, v241 bitop3:0xe4
	s_waitcnt lgkmcnt(10)
	v_mfma_f32_32x32x16_bf16 v[0:15], v[170:173], v[50:53], v[0:15]
	ds_read_b128 v[134:137], v225 offset:0
	v_bitop3_b32 v93, v93, s33, v242 bitop3:0xe4
	v_max3_f32 v243, v243, v74, v90
	v_max3_f32 v248, v248, v75, v91
	v_max3_f32 v243, v243, v76, v92
	v_max3_f32 v248, v248, v77, v93
	v_bfe_i32 v235, v249, 16, 1
	v_bfe_i32 v236, v250, 16, 1
	v_bfe_i32 v237, v249, 17, 1
	v_bfe_i32 v238, v250, 17, 1
	v_bfe_i32 v239, v249, 18, 1
	v_bfe_i32 v240, v250, 18, 1
	v_bfe_i32 v241, v249, 19, 1
	s_waitcnt lgkmcnt(9)
	v_mfma_f32_32x32x16_bf16 v[16:31], v[174:177], v[50:53], v[16:31]
	ds_read_b128 v[138:141], v225 offset:4096
	v_bfe_i32 v242, v250, 19, 1
	v_bitop3_b32 v78, v78, s33, v235 bitop3:0xe4
	v_bitop3_b32 v94, v94, s33, v236 bitop3:0xe4
	v_bitop3_b32 v79, v79, s33, v237 bitop3:0xe4
	v_bitop3_b32 v95, v95, s33, v238 bitop3:0xe4
	v_bitop3_b32 v80, v80, s33, v239 bitop3:0xe4
	v_bitop3_b32 v96, v96, s33, v240 bitop3:0xe4
	v_bitop3_b32 v81, v81, s33, v241 bitop3:0xe4
	v_bitop3_b32 v97, v97, s33, v242 bitop3:0xe4
	v_max3_f32 v243, v243, v78, v94
	v_max3_f32 v248, v248, v79, v95
	v_max3_f32 v243, v243, v80, v96
	s_waitcnt lgkmcnt(8)
	v_mfma_f32_32x32x16_bf16 v[0:15], v[178:181], v[58:61], v[0:15]
	ds_read_b128 v[142:145], v226 offset:0
	v_max3_f32 v248, v248, v81, v97
	v_bfe_i32 v235, v249, 24, 1
	v_bfe_i32 v236, v250, 24, 1
	v_bfe_i32 v237, v249, 25, 1
	v_bfe_i32 v238, v250, 25, 1
	v_bfe_i32 v239, v249, 26, 1
	v_bfe_i32 v240, v250, 26, 1
	v_bfe_i32 v241, v249, 27, 1
	v_bfe_i32 v242, v250, 27, 1
	v_bitop3_b32 v82, v82, s33, v235 bitop3:0xe4
	v_bitop3_b32 v98, v98, s33, v236 bitop3:0xe4
	v_bitop3_b32 v83, v83, s33, v237 bitop3:0xe4
	s_waitcnt lgkmcnt(7)
	v_mfma_f32_32x32x16_bf16 v[16:31], v[182:185], v[58:61], v[16:31]
	ds_read_b128 v[146:149], v226 offset:4096
	v_bitop3_b32 v99, v99, s33, v238 bitop3:0xe4
	v_bitop3_b32 v84, v84, s33, v239 bitop3:0xe4
	v_bitop3_b32 v100, v100, s33, v240 bitop3:0xe4
	v_bitop3_b32 v85, v85, s33, v241 bitop3:0xe4
	v_bitop3_b32 v101, v101, s33, v242 bitop3:0xe4
	v_max3_f32 v243, v243, v82, v98
	v_max3_f32 v248, v248, v83, v99
	v_max3_f32 v243, v243, v84, v100
	v_max3_f32 v248, v248, v85, v101
	v_max_f32_e32 v243, v243, v248
	v_mov_b32_e32 v248, v243
	s_nop 1
	v_permlane32_swap_b32_e32 v243, v248
	v_max3_f32 v243, v230, v243, v248
	v_cmp_neq_f32_e32 vcc, s33, v243
	s_nop 1
	v_cndmask_b32_e32 v248, 0, v243, vcc
	v_sub_f32_e32 v33, v230, v248
	v_mul_f32_e32 v33, 0x3e38aa3b, v33
	v_exp_f32_e32 v232, v33
	v_mul_f32_e32 v234, 0xbe38aa3b, v248
	v_mov_b32_e32 v230, v243
	s_waitcnt vmcnt(3)
	s_barrier
	s_add_u32 s8, s8, 1
	s_cmp_lt_u32 s8, s9
	s_cbranch_scc1 .Lat_loop_3
	s_branch .Lat_epilogue

.Lat_nors_l2:
	v_pk_fma_f32 v[34:35], v[34:35], v[206:207], v[234:235] op_sel_hi:[1,0,0]
	v_pk_fma_f32 v[36:37], v[36:37], v[206:207], v[234:235] op_sel_hi:[1,0,0]
	v_pk_fma_f32 v[38:39], v[38:39], v[206:207], v[234:235] op_sel_hi:[1,0,0]
	ds_read_b64_tr_b16 v[168:169], v228 offset:19456
	s_waitcnt lgkmcnt(14)
	v_pk_fma_f32 v[40:41], v[40:41], v[206:207], v[234:235] op_sel_hi:[1,0,0]
	v_exp_f32_e32 v34, v34
	v_exp_f32_e32 v35, v35
	ds_read_b64_tr_b16 v[170:171], v227 offset:20480
	s_waitcnt lgkmcnt(14)
	v_exp_f32_e32 v36, v36
	v_exp_f32_e32 v37, v37
	v_exp_f32_e32 v38, v38
	ds_read_b64_tr_b16 v[172:173], v227 offset:21504
	s_waitcnt lgkmcnt(14)
	v_exp_f32_e32 v39, v39
	v_exp_f32_e32 v40, v40
	v_exp_f32_e32 v41, v41
	ds_read_b64_tr_b16 v[174:175], v228 offset:20480
	s_waitcnt lgkmcnt(14)
	v_pk_add_f32 v[244:245], v[34:35], v[38:39]
	v_pk_add_f32 v[246:247], v[36:37], v[40:41]
	v_cvt_pk_bf16_f32 v34, v34, v35
	ds_read_b64_tr_b16 v[176:177], v228 offset:21504
	s_waitcnt lgkmcnt(14)
	v_cvt_pk_bf16_f32 v35, v36, v37
	v_cvt_pk_bf16_f32 v36, v38, v39
	v_cvt_pk_bf16_f32 v37, v40, v41
	ds_read_b64_tr_b16 v[178:179], v227 offset:22528
	s_waitcnt lgkmcnt(14)
	s_waitcnt lgkmcnt(11)
	v_mfma_f32_32x32x16_bf16 v[0:15], v[154:157], v[34:37], v[0:15]
	s_waitcnt lgkmcnt(9)
	v_mfma_f32_32x32x16_bf16 v[16:31], v[158:161], v[34:37], v[16:31]
	v_pk_fma_f32 v[42:43], v[42:43], v[206:207], v[234:235] op_sel_hi:[1,0,0]
	v_pk_fma_f32 v[44:45], v[44:45], v[206:207], v[234:235] op_sel_hi:[1,0,0]
	v_pk_fma_f32 v[46:47], v[46:47], v[206:207], v[234:235] op_sel_hi:[1,0,0]
	ds_read_b64_tr_b16 v[180:181], v227 offset:23552
	v_pk_fma_f32 v[48:49], v[48:49], v[206:207], v[234:235] op_sel_hi:[1,0,0]
	v_exp_f32_e32 v42, v42
	v_exp_f32_e32 v43, v43
	ds_read_b64_tr_b16 v[182:183], v228 offset:22528
	v_exp_f32_e32 v44, v44
	v_exp_f32_e32 v45, v45
	v_exp_f32_e32 v46, v46
	ds_read_b64_tr_b16 v[184:185], v228 offset:23552
	v_exp_f32_e32 v47, v47
	v_exp_f32_e32 v48, v48
	v_exp_f32_e32 v49, v49
	v_pk_add_f32 v[244:245], v[244:245], v[42:43]
	v_pk_add_f32 v[246:247], v[246:247], v[44:45]
	v_pk_add_f32 v[244:245], v[244:245], v[46:47]
	v_pk_add_f32 v[246:247], v[246:247], v[48:49]
	v_cvt_pk_bf16_f32 v42, v42, v43
	v_cvt_pk_bf16_f32 v43, v44, v45
	v_cvt_pk_bf16_f32 v44, v46, v47
	v_cvt_pk_bf16_f32 v45, v48, v49
	s_waitcnt lgkmcnt(10)
	v_mfma_f32_32x32x16_bf16 v[0:15], v[162:165], v[42:45], v[0:15]
	s_waitcnt lgkmcnt(8)
	v_mfma_f32_32x32x16_bf16 v[16:31], v[166:169], v[42:45], v[16:31]
	v_pk_fma_f32 v[50:51], v[50:51], v[206:207], v[234:235] op_sel_hi:[1,0,0]
	v_pk_fma_f32 v[52:53], v[52:53], v[206:207], v[234:235] op_sel_hi:[1,0,0]
	v_pk_fma_f32 v[54:55], v[54:55], v[206:207], v[234:235] op_sel_hi:[1,0,0]
	v_pk_fma_f32 v[56:57], v[56:57], v[206:207], v[234:235] op_sel_hi:[1,0,0]
	v_exp_f32_e32 v50, v50
	v_exp_f32_e32 v51, v51
	v_exp_f32_e32 v52, v52
	v_exp_f32_e32 v53, v53
	v_exp_f32_e32 v54, v54
	v_exp_f32_e32 v55, v55
	v_exp_f32_e32 v56, v56
	v_exp_f32_e32 v57, v57
	v_pk_add_f32 v[244:245], v[244:245], v[50:51]
	v_pk_add_f32 v[246:247], v[246:247], v[52:53]
	v_pk_add_f32 v[244:245], v[244:245], v[54:55]
	v_pk_add_f32 v[246:247], v[246:247], v[56:57]
	v_cvt_pk_bf16_f32 v50, v50, v51
	v_cvt_pk_bf16_f32 v51, v52, v53
	v_cvt_pk_bf16_f32 v52, v54, v55
	v_cvt_pk_bf16_f32 v53, v56, v57
	s_waitcnt lgkmcnt(6)
	v_mfma_f32_32x32x16_bf16 v[0:15], v[170:173], v[50:53], v[0:15]
	s_waitcnt lgkmcnt(4)
	v_mfma_f32_32x32x16_bf16 v[16:31], v[174:177], v[50:53], v[16:31]
	v_pk_fma_f32 v[58:59], v[58:59], v[206:207], v[234:235] op_sel_hi:[1,0,0]
	v_pk_fma_f32 v[60:61], v[60:61], v[206:207], v[234:235] op_sel_hi:[1,0,0]
	v_pk_fma_f32 v[62:63], v[62:63], v[206:207], v[234:235] op_sel_hi:[1,0,0]
	v_pk_fma_f32 v[64:65], v[64:65], v[206:207], v[234:235] op_sel_hi:[1,0,0]
	v_exp_f32_e32 v58, v58
	v_exp_f32_e32 v59, v59
	v_exp_f32_e32 v60, v60
	v_exp_f32_e32 v61, v61
	v_exp_f32_e32 v62, v62
	v_exp_f32_e32 v63, v63
	v_exp_f32_e32 v64, v64
	v_exp_f32_e32 v65, v65
	v_pk_add_f32 v[244:245], v[244:245], v[58:59]
	v_pk_add_f32 v[246:247], v[246:247], v[60:61]
	v_pk_add_f32 v[244:245], v[244:245], v[62:63]
	v_pk_add_f32 v[246:247], v[246:247], v[64:65]
	v_cvt_pk_bf16_f32 v58, v58, v59
	v_cvt_pk_bf16_f32 v59, v60, v61
	v_cvt_pk_bf16_f32 v60, v62, v63
	v_cvt_pk_bf16_f32 v61, v64, v65
	v_add_f32_e32 v244, v244, v245
	v_add_f32_e32 v246, v246, v247
	v_add_f32_e32 v244, v244, v246
	v_fma_f32 v231, v231, v232, v244
	s_waitcnt lgkmcnt(2)
	v_mfma_f32_32x32x16_bf16 v[0:15], v[178:181], v[58:61], v[0:15]
	s_waitcnt lgkmcnt(0)
	v_mfma_f32_32x32x16_bf16 v[16:31], v[182:185], v[58:61], v[16:31]
	s_waitcnt vmcnt(3)
	s_barrier
	s_add_u32 s8, s8, 1
	s_cmp_lt_u32 s8, s9
	s_cbranch_scc1 .Lat_loop_3
	s_branch .Lat_epilogue

.Lat_nors_f3:
	v_pk_fma_f32 v[70:71], v[70:71], v[206:207], v[234:235] op_sel_hi:[1,0,0]
	v_pk_fma_f32 v[72:73], v[72:73], v[206:207], v[234:235] op_sel_hi:[1,0,0]
	s_waitcnt lgkmcnt(7)
	v_mfma_f32_32x32x16_bf16 v[34:49], v[118:121], v[102:105], 0
	ds_read_b64_tr_b16 v[154:155], v227 offset:24576
	ds_read_b64_tr_b16 v[156:157], v227 offset:25600
	v_pk_fma_f32 v[74:75], v[74:75], v[206:207], v[234:235] op_sel_hi:[1,0,0]
	v_pk_fma_f32 v[76:77], v[76:77], v[206:207], v[234:235] op_sel_hi:[1,0,0]
	v_exp_f32_e32 v70, v70
	v_exp_f32_e32 v71, v71
	v_exp_f32_e32 v72, v72
	v_exp_f32_e32 v73, v73
	v_exp_f32_e32 v74, v74
	v_exp_f32_e32 v75, v75
	s_waitcnt lgkmcnt(8)
	v_mfma_f32_32x32x16_bf16 v[50:65], v[122:125], v[102:105], 0
	ds_read_b64_tr_b16 v[158:159], v228 offset:24576
	ds_read_b64_tr_b16 v[160:161], v228 offset:25600
	v_exp_f32_e32 v76, v76
	v_exp_f32_e32 v77, v77
	v_pk_add_f32 v[244:245], v[70:71], v[74:75]
	v_pk_add_f32 v[246:247], v[72:73], v[76:77]
	v_cvt_pk_bf16_f32 v70, v70, v71
	v_cvt_pk_bf16_f32 v71, v72, v73
	v_cvt_pk_bf16_f32 v72, v74, v75
	v_cvt_pk_bf16_f32 v73, v76, v77
	v_pk_fma_f32 v[78:79], v[78:79], v[206:207], v[234:235] op_sel_hi:[1,0,0]
	s_waitcnt lgkmcnt(9)
	v_mfma_f32_32x32x16_bf16 v[34:49], v[126:129], v[106:109], v[34:49]
	ds_read_b64_tr_b16 v[162:163], v227 offset:26624
	ds_read_b64_tr_b16 v[164:165], v227 offset:27648
	v_pk_fma_f32 v[80:81], v[80:81], v[206:207], v[234:235] op_sel_hi:[1,0,0]
	v_pk_fma_f32 v[82:83], v[82:83], v[206:207], v[234:235] op_sel_hi:[1,0,0]
	v_pk_fma_f32 v[84:85], v[84:85], v[206:207], v[234:235] op_sel_hi:[1,0,0]
	v_exp_f32_e32 v78, v78
	v_exp_f32_e32 v79, v79
	v_exp_f32_e32 v80, v80
	v_exp_f32_e32 v81, v81
	v_exp_f32_e32 v82, v82
	v_exp_f32_e32 v83, v83
	s_waitcnt lgkmcnt(10)
	v_mfma_f32_32x32x16_bf16 v[50:65], v[130:133], v[106:109], v[50:65]
	ds_read_b64_tr_b16 v[166:167], v228 offset:26624
	ds_read_b64_tr_b16 v[168:169], v228 offset:27648
	v_exp_f32_e32 v84, v84
	v_exp_f32_e32 v85, v85
	v_pk_add_f32 v[244:245], v[244:245], v[78:79]
	v_pk_add_f32 v[246:247], v[246:247], v[80:81]
	v_pk_add_f32 v[244:245], v[244:245], v[82:83]
	v_pk_add_f32 v[246:247], v[246:247], v[84:85]
	v_cvt_pk_bf16_f32 v78, v78, v79
	v_cvt_pk_bf16_f32 v79, v80, v81
	v_cvt_pk_bf16_f32 v80, v82, v83
	s_waitcnt lgkmcnt(11)
	v_mfma_f32_32x32x16_bf16 v[34:49], v[134:137], v[110:113], v[34:49]
	ds_read_b64_tr_b16 v[170:171], v227 offset:28672
	ds_read_b64_tr_b16 v[172:173], v227 offset:29696
	v_cvt_pk_bf16_f32 v81, v84, v85
	v_pk_fma_f32 v[86:87], v[86:87], v[206:207], v[234:235] op_sel_hi:[1,0,0]
	v_pk_fma_f32 v[88:89], v[88:89], v[206:207], v[234:235] op_sel_hi:[1,0,0]
	v_pk_fma_f32 v[90:91], v[90:91], v[206:207], v[234:235] op_sel_hi:[1,0,0]
	v_pk_fma_f32 v[92:93], v[92:93], v[206:207], v[234:235] op_sel_hi:[1,0,0]
	v_exp_f32_e32 v86, v86
	v_exp_f32_e32 v87, v87
	v_exp_f32_e32 v88, v88
	v_exp_f32_e32 v89, v89
	s_waitcnt lgkmcnt(12)
	v_mfma_f32_32x32x16_bf16 v[50:65], v[138:141], v[110:113], v[50:65]
	ds_read_b64_tr_b16 v[174:175], v228 offset:28672
	ds_read_b64_tr_b16 v[176:177], v228 offset:29696
	v_exp_f32_e32 v90, v90
	v_exp_f32_e32 v91, v91
	v_exp_f32_e32 v92, v92
	v_exp_f32_e32 v93, v93
	v_pk_add_f32 v[244:245], v[244:245], v[86:87]
	v_pk_add_f32 v[246:247], v[246:247], v[88:89]
	v_pk_add_f32 v[244:245], v[244:245], v[90:91]
	v_pk_add_f32 v[246:247], v[246:247], v[92:93]
	v_cvt_pk_bf16_f32 v86, v86, v87
	s_waitcnt lgkmcnt(13)
	v_mfma_f32_32x32x16_bf16 v[34:49], v[142:145], v[114:117], v[34:49]
	ds_read_b64_tr_b16 v[178:179], v227 offset:30720
	ds_read_b64_tr_b16 v[180:181], v227 offset:31744
	v_cvt_pk_bf16_f32 v87, v88, v89
	v_cvt_pk_bf16_f32 v88, v90, v91
	v_cvt_pk_bf16_f32 v89, v92, v93
	v_pk_fma_f32 v[94:95], v[94:95], v[206:207], v[234:235] op_sel_hi:[1,0,0]
	v_pk_fma_f32 v[96:97], v[96:97], v[206:207], v[234:235] op_sel_hi:[1,0,0]
	v_pk_fma_f32 v[98:99], v[98:99], v[206:207], v[234:235] op_sel_hi:[1,0,0]
	v_pk_fma_f32 v[100:101], v[100:101], v[206:207], v[234:235] op_sel_hi:[1,0,0]
	v_exp_f32_e32 v94, v94
	v_exp_f32_e32 v95, v95
	s_waitcnt lgkmcnt(14)
	v_mfma_f32_32x32x16_bf16 v[50:65], v[146:149], v[114:117], v[50:65]
	ds_read_b64_tr_b16 v[182:183], v228 offset:30720
	ds_read_b64_tr_b16 v[184:185], v228 offset:31744
	s_waitcnt lgkmcnt(14)
	v_exp_f32_e32 v96, v96
	v_exp_f32_e32 v97, v97
	v_exp_f32_e32 v98, v98
	v_exp_f32_e32 v99, v99
	v_exp_f32_e32 v100, v100
	v_exp_f32_e32 v101, v101
	v_pk_add_f32 v[244:245], v[244:245], v[94:95]
	v_pk_add_f32 v[246:247], v[246:247], v[96:97]
	s_waitcnt lgkmcnt(14)
	v_mfma_f32_32x32x16_bf16 v[0:15], v[154:157], v[70:73], v[0:15]
	ds_read_b128 v[118:121], v223 offset:8192
	v_pk_add_f32 v[244:245], v[244:245], v[98:99]
	v_pk_add_f32 v[246:247], v[246:247], v[100:101]
	v_cvt_pk_bf16_f32 v94, v94, v95
	v_cvt_pk_bf16_f32 v95, v96, v97
	v_cvt_pk_bf16_f32 v96, v98, v99
	v_cvt_pk_bf16_f32 v97, v100, v101
	v_add_f32_e32 v244, v244, v245
	v_add_f32_e32 v246, v246, v247
	v_add_f32_e32 v244, v244, v246
	v_fma_f32 v231, v231, v232, v244
	s_waitcnt vmcnt(4)
	v_lshrrev_b32_e32 v249, v229, v198
	s_waitcnt lgkmcnt(13)
	v_mfma_f32_32x32x16_bf16 v[16:31], v[158:161], v[70:73], v[16:31]
	ds_read_b128 v[122:125], v223 offset:12288
	v_lshrrev_b32_e32 v250, v229, v199
	v_bfe_i32 v235, v249, 0, 1
	v_bfe_i32 v236, v250, 0, 1
	v_bfe_i32 v237, v249, 1, 1
	v_bfe_i32 v238, v250, 1, 1
	v_bfe_i32 v239, v249, 2, 1
	v_bfe_i32 v240, v250, 2, 1
	v_bfe_i32 v241, v249, 3, 1
	v_bfe_i32 v242, v250, 3, 1
	v_bitop3_b32 v34, v34, s33, v235 bitop3:0xe4
	v_bitop3_b32 v50, v50, s33, v236 bitop3:0xe4
	v_bitop3_b32 v35, v35, s33, v237 bitop3:0xe4
	s_waitcnt lgkmcnt(12)
	v_mfma_f32_32x32x16_bf16 v[0:15], v[162:165], v[78:81], v[0:15]
	ds_read_b128 v[126:129], v224 offset:8192
	v_bitop3_b32 v51, v51, s33, v238 bitop3:0xe4
	v_bitop3_b32 v36, v36, s33, v239 bitop3:0xe4
	v_bitop3_b32 v52, v52, s33, v240 bitop3:0xe4
	v_bitop3_b32 v37, v37, s33, v241 bitop3:0xe4
	v_bitop3_b32 v53, v53, s33, v242 bitop3:0xe4
	v_max3_f32 v243, v34, s33, v50
	v_max3_f32 v248, v35, s33, v51
	v_max3_f32 v243, v243, v36, v52
	v_max3_f32 v248, v248, v37, v53
	v_bfe_i32 v235, v249, 8, 1
	v_bfe_i32 v236, v250, 8, 1
	v_bfe_i32 v237, v249, 9, 1
	s_waitcnt lgkmcnt(11)
	v_mfma_f32_32x32x16_bf16 v[16:31], v[166:169], v[78:81], v[16:31]
	ds_read_b128 v[130:133], v224 offset:12288
	v_bfe_i32 v238, v250, 9, 1
	v_bfe_i32 v239, v249, 10, 1
	v_bfe_i32 v240, v250, 10, 1
	v_bfe_i32 v241, v249, 11, 1
	v_bfe_i32 v242, v250, 11, 1
	v_bitop3_b32 v38, v38, s33, v235 bitop3:0xe4
	v_bitop3_b32 v54, v54, s33, v236 bitop3:0xe4
	v_bitop3_b32 v39, v39, s33, v237 bitop3:0xe4
	v_bitop3_b32 v55, v55, s33, v238 bitop3:0xe4
	v_bitop3_b32 v40, v40, s33, v239 bitop3:0xe4
	v_bitop3_b32 v56, v56, s33, v240 bitop3:0xe4
	v_bitop3_b32 v41, v41, s33, v241 bitop3:0xe4
	s_waitcnt lgkmcnt(10)
	v_mfma_f32_32x32x16_bf16 v[0:15], v[170:173], v[86:89], v[0:15]
	ds_read_b128 v[134:137], v225 offset:8192
	v_bitop3_b32 v57, v57, s33, v242 bitop3:0xe4
	v_max3_f32 v243, v243, v38, v54
	v_max3_f32 v248, v248, v39, v55
	v_max3_f32 v243, v243, v40, v56
	v_max3_f32 v248, v248, v41, v57
	v_bfe_i32 v235, v249, 16, 1
	v_bfe_i32 v236, v250, 16, 1
	v_bfe_i32 v237, v249, 17, 1
	v_bfe_i32 v238, v250, 17, 1
	v_bfe_i32 v239, v249, 18, 1
	v_bfe_i32 v240, v250, 18, 1
	v_bfe_i32 v241, v249, 19, 1
	s_waitcnt lgkmcnt(9)
	v_mfma_f32_32x32x16_bf16 v[16:31], v[174:177], v[86:89], v[16:31]
	ds_read_b128 v[138:141], v225 offset:12288
	v_bfe_i32 v242, v250, 19, 1
	v_bitop3_b32 v42, v42, s33, v235 bitop3:0xe4
	v_bitop3_b32 v58, v58, s33, v236 bitop3:0xe4
	v_bitop3_b32 v43, v43, s33, v237 bitop3:0xe4
	v_bitop3_b32 v59, v59, s33, v238 bitop3:0xe4
	v_bitop3_b32 v44, v44, s33, v239 bitop3:0xe4
	v_bitop3_b32 v60, v60, s33, v240 bitop3:0xe4
	v_bitop3_b32 v45, v45, s33, v241 bitop3:0xe4
	v_bitop3_b32 v61, v61, s33, v242 bitop3:0xe4
	v_max3_f32 v243, v243, v42, v58
	v_max3_f32 v248, v248, v43, v59
	v_max3_f32 v243, v243, v44, v60
	s_waitcnt lgkmcnt(8)
	v_mfma_f32_32x32x16_bf16 v[0:15], v[178:181], v[94:97], v[0:15]
	ds_read_b128 v[142:145], v226 offset:8192
	v_max3_f32 v248, v248, v45, v61
	v_bfe_i32 v235, v249, 24, 1
	v_bfe_i32 v236, v250, 24, 1
	v_bfe_i32 v237, v249, 25, 1
	v_bfe_i32 v238, v250, 25, 1
	v_bfe_i32 v239, v249, 26, 1
	v_bfe_i32 v240, v250, 26, 1
	v_bfe_i32 v241, v249, 27, 1
	v_bfe_i32 v242, v250, 27, 1
	v_bitop3_b32 v46, v46, s33, v235 bitop3:0xe4
	v_bitop3_b32 v62, v62, s33, v236 bitop3:0xe4
	v_bitop3_b32 v47, v47, s33, v237 bitop3:0xe4
	s_waitcnt lgkmcnt(7)
	v_mfma_f32_32x32x16_bf16 v[16:31], v[182:185], v[94:97], v[16:31]
	ds_read_b128 v[146:149], v226 offset:12288
	v_bitop3_b32 v63, v63, s33, v238 bitop3:0xe4
	v_bitop3_b32 v48, v48, s33, v239 bitop3:0xe4
	v_bitop3_b32 v64, v64, s33, v240 bitop3:0xe4
	v_bitop3_b32 v49, v49, s33, v241 bitop3:0xe4
	v_bitop3_b32 v65, v65, s33, v242 bitop3:0xe4
	v_max3_f32 v243, v243, v46, v62
	v_max3_f32 v248, v248, v47, v63
	v_max3_f32 v243, v243, v48, v64
	v_max3_f32 v248, v248, v49, v65
	v_max_f32_e32 v243, v243, v248
	v_mov_b32_e32 v248, v243
	s_nop 1
	v_permlane32_swap_b32_e32 v243, v248
	v_max3_f32 v243, v230, v243, v248
	v_cmp_neq_f32_e32 vcc, s33, v243
	s_nop 1
	v_cndmask_b32_e32 v248, 0, v243, vcc
	v_sub_f32_e32 v33, v230, v248
	v_mul_f32_e32 v33, 0x3e38aa3b, v33
	v_exp_f32_e32 v232, v33
	v_mul_f32_e32 v234, 0xbe38aa3b, v248
	v_mov_b32_e32 v230, v243
	s_waitcnt vmcnt(2)
	s_barrier
	s_add_u32 s8, s8, 1
	s_cmp_lt_u32 s8, s9
	s_cbranch_scc1 .Lat_loop_0
	s_branch .Lat_epilogue

.Lat_nors_l3:
	v_pk_fma_f32 v[70:71], v[70:71], v[206:207], v[234:235] op_sel_hi:[1,0,0]
	v_pk_fma_f32 v[72:73], v[72:73], v[206:207], v[234:235] op_sel_hi:[1,0,0]
	v_pk_fma_f32 v[74:75], v[74:75], v[206:207], v[234:235] op_sel_hi:[1,0,0]
	ds_read_b64_tr_b16 v[168:169], v228 offset:27648
	s_waitcnt lgkmcnt(14)
	v_pk_fma_f32 v[76:77], v[76:77], v[206:207], v[234:235] op_sel_hi:[1,0,0]
	v_exp_f32_e32 v70, v70
	v_exp_f32_e32 v71, v71
	ds_read_b64_tr_b16 v[170:171], v227 offset:28672
	s_waitcnt lgkmcnt(14)
	v_exp_f32_e32 v72, v72
	v_exp_f32_e32 v73, v73
	v_exp_f32_e32 v74, v74
	ds_read_b64_tr_b16 v[172:173], v227 offset:29696
	s_waitcnt lgkmcnt(14)
	v_exp_f32_e32 v75, v75
	v_exp_f32_e32 v76, v76
	v_exp_f32_e32 v77, v77
	ds_read_b64_tr_b16 v[174:175], v228 offset:28672
	s_waitcnt lgkmcnt(14)
	v_pk_add_f32 v[244:245], v[70:71], v[74:75]
	v_pk_add_f32 v[246:247], v[72:73], v[76:77]
	v_cvt_pk_bf16_f32 v70, v70, v71
	ds_read_b64_tr_b16 v[176:177], v228 offset:29696
	s_waitcnt lgkmcnt(14)
	v_cvt_pk_bf16_f32 v71, v72, v73
	v_cvt_pk_bf16_f32 v72, v74, v75
	v_cvt_pk_bf16_f32 v73, v76, v77
	ds_read_b64_tr_b16 v[178:179], v227 offset:30720
	s_waitcnt lgkmcnt(14)
	s_waitcnt lgkmcnt(11)
	v_mfma_f32_32x32x16_bf16 v[0:15], v[154:157], v[70:73], v[0:15]
	s_waitcnt lgkmcnt(9)
	v_mfma_f32_32x32x16_bf16 v[16:31], v[158:161], v[70:73], v[16:31]
	v_pk_fma_f32 v[78:79], v[78:79], v[206:207], v[234:235] op_sel_hi:[1,0,0]
	v_pk_fma_f32 v[80:81], v[80:81], v[206:207], v[234:235] op_sel_hi:[1,0,0]
	v_pk_fma_f32 v[82:83], v[82:83], v[206:207], v[234:235] op_sel_hi:[1,0,0]
	ds_read_b64_tr_b16 v[180:181], v227 offset:31744
	v_pk_fma_f32 v[84:85], v[84:85], v[206:207], v[234:235] op_sel_hi:[1,0,0]
	v_exp_f32_e32 v78, v78
	v_exp_f32_e32 v79, v79
	ds_read_b64_tr_b16 v[182:183], v228 offset:30720
	v_exp_f32_e32 v80, v80
	v_exp_f32_e32 v81, v81
	v_exp_f32_e32 v82, v82
	ds_read_b64_tr_b16 v[184:185], v228 offset:31744
	v_exp_f32_e32 v83, v83
	v_exp_f32_e32 v84, v84
	v_exp_f32_e32 v85, v85
	v_pk_add_f32 v[244:245], v[244:245], v[78:79]
	v_pk_add_f32 v[246:247], v[246:247], v[80:81]
	v_pk_add_f32 v[244:245], v[244:245], v[82:83]
	v_pk_add_f32 v[246:247], v[246:247], v[84:85]
	v_cvt_pk_bf16_f32 v78, v78, v79
	v_cvt_pk_bf16_f32 v79, v80, v81
	v_cvt_pk_bf16_f32 v80, v82, v83
	v_cvt_pk_bf16_f32 v81, v84, v85
	s_waitcnt lgkmcnt(10)
	v_mfma_f32_32x32x16_bf16 v[0:15], v[162:165], v[78:81], v[0:15]
	s_waitcnt lgkmcnt(8)
	v_mfma_f32_32x32x16_bf16 v[16:31], v[166:169], v[78:81], v[16:31]
	v_pk_fma_f32 v[86:87], v[86:87], v[206:207], v[234:235] op_sel_hi:[1,0,0]
	v_pk_fma_f32 v[88:89], v[88:89], v[206:207], v[234:235] op_sel_hi:[1,0,0]
	v_pk_fma_f32 v[90:91], v[90:91], v[206:207], v[234:235] op_sel_hi:[1,0,0]
	v_pk_fma_f32 v[92:93], v[92:93], v[206:207], v[234:235] op_sel_hi:[1,0,0]
	v_exp_f32_e32 v86, v86
	v_exp_f32_e32 v87, v87
	v_exp_f32_e32 v88, v88
	v_exp_f32_e32 v89, v89
	v_exp_f32_e32 v90, v90
	v_exp_f32_e32 v91, v91
	v_exp_f32_e32 v92, v92
	v_exp_f32_e32 v93, v93
	v_pk_add_f32 v[244:245], v[244:245], v[86:87]
	v_pk_add_f32 v[246:247], v[246:247], v[88:89]
	v_pk_add_f32 v[244:245], v[244:245], v[90:91]
	v_pk_add_f32 v[246:247], v[246:247], v[92:93]
	v_cvt_pk_bf16_f32 v86, v86, v87
	v_cvt_pk_bf16_f32 v87, v88, v89
	v_cvt_pk_bf16_f32 v88, v90, v91
	v_cvt_pk_bf16_f32 v89, v92, v93
	s_waitcnt lgkmcnt(6)
	v_mfma_f32_32x32x16_bf16 v[0:15], v[170:173], v[86:89], v[0:15]
	s_waitcnt lgkmcnt(4)
	v_mfma_f32_32x32x16_bf16 v[16:31], v[174:177], v[86:89], v[16:31]
	v_pk_fma_f32 v[94:95], v[94:95], v[206:207], v[234:235] op_sel_hi:[1,0,0]
	v_pk_fma_f32 v[96:97], v[96:97], v[206:207], v[234:235] op_sel_hi:[1,0,0]
	v_pk_fma_f32 v[98:99], v[98:99], v[206:207], v[234:235] op_sel_hi:[1,0,0]
	v_pk_fma_f32 v[100:101], v[100:101], v[206:207], v[234:235] op_sel_hi:[1,0,0]
	v_exp_f32_e32 v94, v94
	v_exp_f32_e32 v95, v95
	v_exp_f32_e32 v96, v96
	v_exp_f32_e32 v97, v97
	v_exp_f32_e32 v98, v98
	v_exp_f32_e32 v99, v99
	v_exp_f32_e32 v100, v100
	v_exp_f32_e32 v101, v101
	v_pk_add_f32 v[244:245], v[244:245], v[94:95]
	v_pk_add_f32 v[246:247], v[246:247], v[96:97]
	v_pk_add_f32 v[244:245], v[244:245], v[98:99]
	v_pk_add_f32 v[246:247], v[246:247], v[100:101]
	v_cvt_pk_bf16_f32 v94, v94, v95
	v_cvt_pk_bf16_f32 v95, v96, v97
	v_cvt_pk_bf16_f32 v96, v98, v99
	v_cvt_pk_bf16_f32 v97, v100, v101
	v_add_f32_e32 v244, v244, v245
	v_add_f32_e32 v246, v246, v247
	v_add_f32_e32 v244, v244, v246
	v_fma_f32 v231, v231, v232, v244
	s_waitcnt lgkmcnt(2)
	v_mfma_f32_32x32x16_bf16 v[0:15], v[178:181], v[94:97], v[0:15]
	s_waitcnt lgkmcnt(0)
	v_mfma_f32_32x32x16_bf16 v[16:31], v[182:185], v[94:97], v[16:31]
	s_waitcnt vmcnt(2)
	s_barrier
	s_add_u32 s8, s8, 1
	s_cmp_lt_u32 s8, s9
	s_cbranch_scc1 .Lat_loop_0
	s_branch .Lat_epilogue
